# layer-0 out-proj epilogue: the four f32 residual loads of each row block issued together (were a load-wait ladder of 32 HBM/L2 round trips)
# baseline (speedup 1.0000x reference)
; DEVI void phase_resid_gemm(const Params& p, const bfu* A, int lda, int nkt, const bfu* wT, int ldb, const float* resid32,
;                            float* ssq_out, float* out32, char* lds) {
;     ...
;     for (int mi = 0; mi < 8; ++mi) {
;       const int m = m0 + wm * 128 + mi * 16 + fr;
;       float ss = 0.f;
; #pragma unroll
;       for (int ni = 0; ni < 4; ++ni) {
;         const int n = n0 + wn * 64 + ni * 16 + fq * 4;
;         float4 r;
;         if (resid32) r = *(const float4*)(resid32 + (long)m * 1024 + n);
.LBB0_240:
	s_lshl_b32 s20, s25, 8
	v_add_u32_e32 v132, s20, v179
	v_ashrrev_i32_e32 v133, 31, v132
	v_or_b32_e32 v130, s27, v181
	v_lshlrev_b64 v[126:127], 12, v[132:133]
	v_lshl_add_u64 v[126:127], s[0:1], 0, v[126:127]
	v_ashrrev_i32_e32 v131, 31, v130
	v_cndmask_b32_e64 v0, 0, 1, s[4:5]
	v_cmp_ne_u32_e64 s[40:41], 1, v0
	s_andn2_b64 vcc, exec, s[4:5]
	v_lshl_add_u64 v[136:137], v[130:131], 2, v[126:127]
	s_cbranch_vccnz .LBB0_247
	global_load_dwordx4 v[126:129], v[136:137], off nt
	global_load_dwordx4 v[234:237], v[136:137], off offset:64 nt
	global_load_dwordx4 v[238:241], v[136:137], off offset:128 nt
	global_load_dwordx4 v[246:249], v[136:137], off offset:192 nt
	s_mov_b64 s[36:37], 0
	s_branch .LBB0_248

; DEVI float lo2f(unsigned u) { return __uint_as_float(u << 16); }
; DEVI float hi2f(unsigned u) { return __uint_as_float(u & 0xffff0000u); }
; DEVI void phase_resid_gemm(const Params& p, const bfu* A, int lda, int nkt, const bfu* wT, int ldb, const float* resid32,
;                            float* ssq_out, float* out32, char* lds) {
;     ...
;         if (resid32) r = *(const float4*)(resid32 + (long)m * 1024 + n);
;         else { const uint2 u = *(const uint2*)(xs + (long)m * LDX + n); r = make_float4(lo2f(u.x), hi2f(u.x), lo2f(u.y), hi2f(u.y)); }
;         float4 o;
;         o.x = r.x + acc[ni][mi][0]; o.y = r.y + acc[ni][mi][1]; o.z = r.z + acc[ni][mi][2]; o.w = r.w + acc[ni][mi][3];
;         if (out32) *(float4*)(out32 + (long)m * 1024 + n) = o;
;         else {
;           uint2 ob; ob.x = pack2(o.x, o.y); ob.y = pack2(o.z, o.w);
;           *(uint2*)(xs + (long)m * LDX + n) = ob;
;           const float q0 = lo2f(ob.x), q1 = hi2f(ob.x), q2 = lo2f(ob.y), q3 = hi2f(ob.y);
.LBB0_250:
	s_waitcnt vmcnt(0)
	v_pk_add_f32 v[126:127], v[162:163], v[126:127]
	v_pk_add_f32 v[128:129], v[164:165], v[128:129]
	v_cvt_pk_bf16_f32 v138, v126, v127
	v_cvt_pk_bf16_f32 v139, v128, v129
	s_and_b64 vcc, exec, s[40:41]
	v_mov_b32_e32 v200, v138
	v_mov_b32_e32 v201, v139
	s_cbranch_vccnz .LBB0_263
	v_mov_b32_e32 v126, v234
	v_mov_b32_e32 v127, v235
	v_mov_b32_e32 v128, v236
	v_mov_b32_e32 v129, v237
	s_cbranch_execnz .LBB0_253

; DEVI float lo2f(unsigned u) { return __uint_as_float(u << 16); }
; DEVI float hi2f(unsigned u) { return __uint_as_float(u & 0xffff0000u); }
; DEVI void phase_resid_gemm(const Params& p, const bfu* A, int lda, int nkt, const bfu* wT, int ldb, const float* resid32,
;                            float* ssq_out, float* out32, char* lds) {
;     ...
;         if (resid32) r = *(const float4*)(resid32 + (long)m * 1024 + n);
;         else { const uint2 u = *(const uint2*)(xs + (long)m * LDX + n); r = make_float4(lo2f(u.x), hi2f(u.x), lo2f(u.y), hi2f(u.y)); }
;         float4 o;
;         o.x = r.x + acc[ni][mi][0]; o.y = r.y + acc[ni][mi][1]; o.z = r.z + acc[ni][mi][2]; o.w = r.w + acc[ni][mi][3];
;         if (out32) *(float4*)(out32 + (long)m * 1024 + n) = o;
;         else {
;           uint2 ob; ob.x = pack2(o.x, o.y); ob.y = pack2(o.z, o.w);
;           *(uint2*)(xs + (long)m * LDX + n) = ob;
;           const float q0 = lo2f(ob.x), q1 = hi2f(ob.x), q2 = lo2f(ob.y), q3 = hi2f(ob.y);
.LBB0_253:
	s_waitcnt vmcnt(0)
	v_pk_add_f32 v[122:123], v[122:123], v[126:127]
	v_pk_add_f32 v[124:125], v[124:125], v[128:129]
	v_cvt_pk_bf16_f32 v126, v122, v123
	v_cvt_pk_bf16_f32 v127, v124, v125
	s_and_b64 vcc, exec, s[40:41]
	v_mov_b32_e32 v206, v126
	v_mov_b32_e32 v207, v127
	v_mov_b32_e32 v204, v200
	v_mov_b32_e32 v205, v201
	v_lshl_add_u64 v[212:213], v[134:135], 0, v[254:255]
	s_nop 0
	v_permlane16_swap_b32_e32 v204, v206
	v_permlane16_swap_b32_e32 v205, v207
	s_nop 1
	global_store_dwordx4 v[212:213], v[204:207], off
	s_cbranch_vccnz .LBB0_264
	v_mov_b32_e32 v122, v238
	v_mov_b32_e32 v123, v239
	v_mov_b32_e32 v124, v240
	v_mov_b32_e32 v125, v241
	s_cbranch_execnz .LBB0_256

; DEVI float lo2f(unsigned u) { return __uint_as_float(u << 16); }
; DEVI float hi2f(unsigned u) { return __uint_as_float(u & 0xffff0000u); }
; DEVI void phase_resid_gemm(const Params& p, const bfu* A, int lda, int nkt, const bfu* wT, int ldb, const float* resid32,
;                            float* ssq_out, float* out32, char* lds) {
;     ...
;         if (resid32) r = *(const float4*)(resid32 + (long)m * 1024 + n);
;         else { const uint2 u = *(const uint2*)(xs + (long)m * LDX + n); r = make_float4(lo2f(u.x), hi2f(u.x), lo2f(u.y), hi2f(u.y)); }
;         float4 o;
;         o.x = r.x + acc[ni][mi][0]; o.y = r.y + acc[ni][mi][1]; o.z = r.z + acc[ni][mi][2]; o.w = r.w + acc[ni][mi][3];
;         if (out32) *(float4*)(out32 + (long)m * 1024 + n) = o;
;         else {
;           uint2 ob; ob.x = pack2(o.x, o.y); ob.y = pack2(o.z, o.w);
;           *(uint2*)(xs + (long)m * LDX + n) = ob;
;           const float q0 = lo2f(ob.x), q1 = hi2f(ob.x), q2 = lo2f(ob.y), q3 = hi2f(ob.y);
.LBB0_256:
	s_waitcnt vmcnt(0)
	v_pk_add_f32 v[118:119], v[118:119], v[122:123]
	v_pk_add_f32 v[120:121], v[120:121], v[124:125]
	v_cvt_pk_bf16_f32 v122, v118, v119
	v_cvt_pk_bf16_f32 v123, v120, v121
	s_and_b64 vcc, exec, s[40:41]
	v_mov_b32_e32 v200, v122
	v_mov_b32_e32 v201, v123
	s_cbranch_vccnz .LBB0_265
	v_mov_b32_e32 v118, v246
	v_mov_b32_e32 v119, v247
	v_mov_b32_e32 v120, v248
	v_mov_b32_e32 v121, v249
	s_cbranch_execnz .LBB0_259

; DEVI void phase_resid_gemm(const Params& p, const bfu* A, int lda, int nkt, const bfu* wT, int ldb, const float* resid32,
;                            float* ssq_out, float* out32, char* lds) {
;     ...
;     for (int mi = 0; mi < 8; ++mi) {
;       const int m = m0 + wm * 128 + mi * 16 + fr;
;       float ss = 0.f;
; #pragma unroll
;       for (int ni = 0; ni < 4; ++ni) {
;         const int n = n0 + wn * 64 + ni * 16 + fq * 4;
;         float4 r;
;         if (resid32) r = *(const float4*)(resid32 + (long)m * 1024 + n);
.LBB0_261:
	s_or_b64 exec, exec, s[36:37]
	v_or_b32_e32 v118, 16, v132
	v_ashrrev_i32_e32 v119, 31, v118
	s_waitcnt lgkmcnt(0)
	v_lshlrev_b64 v[110:111], 12, v[118:119]
	v_lshl_add_u64 v[110:111], s[0:1], 0, v[110:111]
	s_and_b64 vcc, exec, s[40:41]
	v_lshl_add_u64 v[120:121], v[130:131], 2, v[110:111]
	s_cbranch_vccnz .LBB0_266
	global_load_dwordx4 v[110:113], v[120:121], off nt
	global_load_dwordx4 v[234:237], v[120:121], off offset:64 nt
	global_load_dwordx4 v[238:241], v[120:121], off offset:128 nt
	global_load_dwordx4 v[246:249], v[120:121], off offset:192 nt
	s_mov_b64 s[36:37], 0
	s_branch .LBB0_267

; DEVI float lo2f(unsigned u) { return __uint_as_float(u << 16); }
; DEVI float hi2f(unsigned u) { return __uint_as_float(u & 0xffff0000u); }
; DEVI void phase_resid_gemm(const Params& p, const bfu* A, int lda, int nkt, const bfu* wT, int ldb, const float* resid32,
;                            float* ssq_out, float* out32, char* lds) {
;     ...
;         if (resid32) r = *(const float4*)(resid32 + (long)m * 1024 + n);
;         else { const uint2 u = *(const uint2*)(xs + (long)m * LDX + n); r = make_float4(lo2f(u.x), hi2f(u.x), lo2f(u.y), hi2f(u.y)); }
;         float4 o;
;         o.x = r.x + acc[ni][mi][0]; o.y = r.y + acc[ni][mi][1]; o.z = r.z + acc[ni][mi][2]; o.w = r.w + acc[ni][mi][3];
;         if (out32) *(float4*)(out32 + (long)m * 1024 + n) = o;
;         else {
;           uint2 ob; ob.x = pack2(o.x, o.y); ob.y = pack2(o.z, o.w);
;           *(uint2*)(xs + (long)m * LDX + n) = ob;
;           const float q0 = lo2f(ob.x), q1 = hi2f(ob.x), q2 = lo2f(ob.y), q3 = hi2f(ob.y);
.LBB0_269:
	s_waitcnt vmcnt(0)
	v_pk_add_f32 v[110:111], v[114:115], v[110:111]
	v_pk_add_f32 v[112:113], v[116:117], v[112:113]
	v_cvt_pk_bf16_f32 v114, v110, v111
	v_cvt_pk_bf16_f32 v115, v112, v113
	s_and_b64 vcc, exec, s[40:41]
	v_mov_b32_e32 v200, v114
	v_mov_b32_e32 v201, v115
	s_cbranch_vccnz .LBB0_282
	v_mov_b32_e32 v110, v234
	v_mov_b32_e32 v111, v235
	v_mov_b32_e32 v112, v236
	v_mov_b32_e32 v113, v237
	s_cbranch_execnz .LBB0_272

; DEVI float lo2f(unsigned u) { return __uint_as_float(u << 16); }
; DEVI float hi2f(unsigned u) { return __uint_as_float(u & 0xffff0000u); }
; DEVI void phase_resid_gemm(const Params& p, const bfu* A, int lda, int nkt, const bfu* wT, int ldb, const float* resid32,
;                            float* ssq_out, float* out32, char* lds) {
;     ...
;         if (resid32) r = *(const float4*)(resid32 + (long)m * 1024 + n);
;         else { const uint2 u = *(const uint2*)(xs + (long)m * LDX + n); r = make_float4(lo2f(u.x), hi2f(u.x), lo2f(u.y), hi2f(u.y)); }
;         float4 o;
;         o.x = r.x + acc[ni][mi][0]; o.y = r.y + acc[ni][mi][1]; o.z = r.z + acc[ni][mi][2]; o.w = r.w + acc[ni][mi][3];
;         if (out32) *(float4*)(out32 + (long)m * 1024 + n) = o;
;         else {
;           uint2 ob; ob.x = pack2(o.x, o.y); ob.y = pack2(o.z, o.w);
;           *(uint2*)(xs + (long)m * LDX + n) = ob;
;           const float q0 = lo2f(ob.x), q1 = hi2f(ob.x), q2 = lo2f(ob.y), q3 = hi2f(ob.y);
.LBB0_272:
	s_waitcnt vmcnt(0)
	v_pk_add_f32 v[106:107], v[106:107], v[110:111]
	v_pk_add_f32 v[108:109], v[108:109], v[112:113]
	v_cvt_pk_bf16_f32 v110, v106, v107
	v_cvt_pk_bf16_f32 v111, v108, v109
	s_and_b64 vcc, exec, s[40:41]
	v_mov_b32_e32 v206, v110
	v_mov_b32_e32 v207, v111
	v_mov_b32_e32 v204, v200
	v_mov_b32_e32 v205, v201
	v_lshl_add_u64 v[212:213], v[118:119], 0, v[254:255]
	s_nop 0
	v_permlane16_swap_b32_e32 v204, v206
	v_permlane16_swap_b32_e32 v205, v207
	s_nop 1
	global_store_dwordx4 v[212:213], v[204:207], off
	s_cbranch_vccnz .LBB0_283
	v_mov_b32_e32 v106, v238
	v_mov_b32_e32 v107, v239
	v_mov_b32_e32 v108, v240
	v_mov_b32_e32 v109, v241
	s_cbranch_execnz .LBB0_275

; DEVI float lo2f(unsigned u) { return __uint_as_float(u << 16); }
; DEVI float hi2f(unsigned u) { return __uint_as_float(u & 0xffff0000u); }
; DEVI void phase_resid_gemm(const Params& p, const bfu* A, int lda, int nkt, const bfu* wT, int ldb, const float* resid32,
;                            float* ssq_out, float* out32, char* lds) {
;     ...
;         if (resid32) r = *(const float4*)(resid32 + (long)m * 1024 + n);
;         else { const uint2 u = *(const uint2*)(xs + (long)m * LDX + n); r = make_float4(lo2f(u.x), hi2f(u.x), lo2f(u.y), hi2f(u.y)); }
;         float4 o;
;         o.x = r.x + acc[ni][mi][0]; o.y = r.y + acc[ni][mi][1]; o.z = r.z + acc[ni][mi][2]; o.w = r.w + acc[ni][mi][3];
;         if (out32) *(float4*)(out32 + (long)m * 1024 + n) = o;
;         else {
;           uint2 ob; ob.x = pack2(o.x, o.y); ob.y = pack2(o.z, o.w);
;           *(uint2*)(xs + (long)m * LDX + n) = ob;
;           const float q0 = lo2f(ob.x), q1 = hi2f(ob.x), q2 = lo2f(ob.y), q3 = hi2f(ob.y);
.LBB0_275:
	s_waitcnt vmcnt(0)
	v_pk_add_f32 v[102:103], v[102:103], v[106:107]
	v_pk_add_f32 v[104:105], v[104:105], v[108:109]
	v_cvt_pk_bf16_f32 v106, v102, v103
	v_cvt_pk_bf16_f32 v107, v104, v105
	s_and_b64 vcc, exec, s[40:41]
	v_mov_b32_e32 v200, v106
	v_mov_b32_e32 v201, v107
	s_cbranch_vccnz .LBB0_284
	v_mov_b32_e32 v102, v246
	v_mov_b32_e32 v103, v247
	v_mov_b32_e32 v104, v248
	v_mov_b32_e32 v105, v249
	s_cbranch_execnz .LBB0_278

; DEVI void phase_resid_gemm(const Params& p, const bfu* A, int lda, int nkt, const bfu* wT, int ldb, const float* resid32,
;                            float* ssq_out, float* out32, char* lds) {
;     ...
;     for (int mi = 0; mi < 8; ++mi) {
;       const int m = m0 + wm * 128 + mi * 16 + fr;
;       float ss = 0.f;
; #pragma unroll
;       for (int ni = 0; ni < 4; ++ni) {
;         const int n = n0 + wn * 64 + ni * 16 + fq * 4;
;         float4 r;
;         if (resid32) r = *(const float4*)(resid32 + (long)m * 1024 + n);
.LBB0_280:
	s_or_b64 exec, exec, s[36:37]
	v_or_b32_e32 v102, 32, v132
	v_ashrrev_i32_e32 v103, 31, v102
	s_waitcnt lgkmcnt(0)
	v_lshlrev_b64 v[94:95], 12, v[102:103]
	v_lshl_add_u64 v[94:95], s[0:1], 0, v[94:95]
	s_and_b64 vcc, exec, s[40:41]
	v_lshl_add_u64 v[104:105], v[130:131], 2, v[94:95]
	s_cbranch_vccnz .LBB0_285
	global_load_dwordx4 v[94:97], v[104:105], off nt
	global_load_dwordx4 v[234:237], v[104:105], off offset:64 nt
	global_load_dwordx4 v[238:241], v[104:105], off offset:128 nt
	global_load_dwordx4 v[246:249], v[104:105], off offset:192 nt
	s_mov_b64 s[36:37], 0
	s_branch .LBB0_286

; DEVI float lo2f(unsigned u) { return __uint_as_float(u << 16); }
; DEVI float hi2f(unsigned u) { return __uint_as_float(u & 0xffff0000u); }
; DEVI void phase_resid_gemm(const Params& p, const bfu* A, int lda, int nkt, const bfu* wT, int ldb, const float* resid32,
;                            float* ssq_out, float* out32, char* lds) {
;     ...
;         if (resid32) r = *(const float4*)(resid32 + (long)m * 1024 + n);
;         else { const uint2 u = *(const uint2*)(xs + (long)m * LDX + n); r = make_float4(lo2f(u.x), hi2f(u.x), lo2f(u.y), hi2f(u.y)); }
;         float4 o;
;         o.x = r.x + acc[ni][mi][0]; o.y = r.y + acc[ni][mi][1]; o.z = r.z + acc[ni][mi][2]; o.w = r.w + acc[ni][mi][3];
;         if (out32) *(float4*)(out32 + (long)m * 1024 + n) = o;
;         else {
;           uint2 ob; ob.x = pack2(o.x, o.y); ob.y = pack2(o.z, o.w);
;           *(uint2*)(xs + (long)m * LDX + n) = ob;
;           const float q0 = lo2f(ob.x), q1 = hi2f(ob.x), q2 = lo2f(ob.y), q3 = hi2f(ob.y);
.LBB0_288:
	s_waitcnt vmcnt(0)
	v_pk_add_f32 v[94:95], v[98:99], v[94:95]
	v_pk_add_f32 v[96:97], v[100:101], v[96:97]
	v_cvt_pk_bf16_f32 v98, v94, v95
	v_cvt_pk_bf16_f32 v99, v96, v97
	s_and_b64 vcc, exec, s[40:41]
	v_mov_b32_e32 v200, v98
	v_mov_b32_e32 v201, v99
	s_cbranch_vccnz .LBB0_301
	v_mov_b32_e32 v94, v234
	v_mov_b32_e32 v95, v235
	v_mov_b32_e32 v96, v236
	v_mov_b32_e32 v97, v237
	s_cbranch_execnz .LBB0_291

; DEVI float lo2f(unsigned u) { return __uint_as_float(u << 16); }
; DEVI float hi2f(unsigned u) { return __uint_as_float(u & 0xffff0000u); }
; DEVI void phase_resid_gemm(const Params& p, const bfu* A, int lda, int nkt, const bfu* wT, int ldb, const float* resid32,
;                            float* ssq_out, float* out32, char* lds) {
;     ...
;         if (resid32) r = *(const float4*)(resid32 + (long)m * 1024 + n);
;         else { const uint2 u = *(const uint2*)(xs + (long)m * LDX + n); r = make_float4(lo2f(u.x), hi2f(u.x), lo2f(u.y), hi2f(u.y)); }
;         float4 o;
;         o.x = r.x + acc[ni][mi][0]; o.y = r.y + acc[ni][mi][1]; o.z = r.z + acc[ni][mi][2]; o.w = r.w + acc[ni][mi][3];
;         if (out32) *(float4*)(out32 + (long)m * 1024 + n) = o;
;         else {
;           uint2 ob; ob.x = pack2(o.x, o.y); ob.y = pack2(o.z, o.w);
;           *(uint2*)(xs + (long)m * LDX + n) = ob;
;           const float q0 = lo2f(ob.x), q1 = hi2f(ob.x), q2 = lo2f(ob.y), q3 = hi2f(ob.y);
.LBB0_291:
	s_waitcnt vmcnt(0)
	v_pk_add_f32 v[90:91], v[90:91], v[94:95]
	v_pk_add_f32 v[92:93], v[92:93], v[96:97]
	v_cvt_pk_bf16_f32 v94, v90, v91
	v_cvt_pk_bf16_f32 v95, v92, v93
	s_and_b64 vcc, exec, s[40:41]
	v_mov_b32_e32 v206, v94
	v_mov_b32_e32 v207, v95
	v_mov_b32_e32 v204, v200
	v_mov_b32_e32 v205, v201
	v_lshl_add_u64 v[212:213], v[102:103], 0, v[254:255]
	s_nop 0
	v_permlane16_swap_b32_e32 v204, v206
	v_permlane16_swap_b32_e32 v205, v207
	s_nop 1
	global_store_dwordx4 v[212:213], v[204:207], off
	s_cbranch_vccnz .LBB0_302
	v_mov_b32_e32 v90, v238
	v_mov_b32_e32 v91, v239
	v_mov_b32_e32 v92, v240
	v_mov_b32_e32 v93, v241
	s_cbranch_execnz .LBB0_294

; DEVI float lo2f(unsigned u) { return __uint_as_float(u << 16); }
; DEVI float hi2f(unsigned u) { return __uint_as_float(u & 0xffff0000u); }
; DEVI void phase_resid_gemm(const Params& p, const bfu* A, int lda, int nkt, const bfu* wT, int ldb, const float* resid32,
;                            float* ssq_out, float* out32, char* lds) {
;     ...
;         if (resid32) r = *(const float4*)(resid32 + (long)m * 1024 + n);
;         else { const uint2 u = *(const uint2*)(xs + (long)m * LDX + n); r = make_float4(lo2f(u.x), hi2f(u.x), lo2f(u.y), hi2f(u.y)); }
;         float4 o;
;         o.x = r.x + acc[ni][mi][0]; o.y = r.y + acc[ni][mi][1]; o.z = r.z + acc[ni][mi][2]; o.w = r.w + acc[ni][mi][3];
;         if (out32) *(float4*)(out32 + (long)m * 1024 + n) = o;
;         else {
;           uint2 ob; ob.x = pack2(o.x, o.y); ob.y = pack2(o.z, o.w);
;           *(uint2*)(xs + (long)m * LDX + n) = ob;
;           const float q0 = lo2f(ob.x), q1 = hi2f(ob.x), q2 = lo2f(ob.y), q3 = hi2f(ob.y);
.LBB0_294:
	s_waitcnt vmcnt(0)
	v_pk_add_f32 v[86:87], v[86:87], v[90:91]
	v_pk_add_f32 v[88:89], v[88:89], v[92:93]
	v_cvt_pk_bf16_f32 v90, v86, v87
	v_cvt_pk_bf16_f32 v91, v88, v89
	s_and_b64 vcc, exec, s[40:41]
	v_mov_b32_e32 v200, v90
	v_mov_b32_e32 v201, v91
	s_cbranch_vccnz .LBB0_303
	v_mov_b32_e32 v86, v246
	v_mov_b32_e32 v87, v247
	v_mov_b32_e32 v88, v248
	v_mov_b32_e32 v89, v249
	s_cbranch_execnz .LBB0_297

; DEVI void phase_resid_gemm(const Params& p, const bfu* A, int lda, int nkt, const bfu* wT, int ldb, const float* resid32,
;                            float* ssq_out, float* out32, char* lds) {
;     ...
;     for (int mi = 0; mi < 8; ++mi) {
;       const int m = m0 + wm * 128 + mi * 16 + fr;
;       float ss = 0.f;
; #pragma unroll
;       for (int ni = 0; ni < 4; ++ni) {
;         const int n = n0 + wn * 64 + ni * 16 + fq * 4;
;         float4 r;
;         if (resid32) r = *(const float4*)(resid32 + (long)m * 1024 + n);
.LBB0_299:
	s_or_b64 exec, exec, s[36:37]
	v_or_b32_e32 v86, 48, v132
	v_ashrrev_i32_e32 v87, 31, v86
	s_waitcnt lgkmcnt(0)
	v_lshlrev_b64 v[78:79], 12, v[86:87]
	v_lshl_add_u64 v[78:79], s[0:1], 0, v[78:79]
	s_and_b64 vcc, exec, s[40:41]
	v_lshl_add_u64 v[88:89], v[130:131], 2, v[78:79]
	s_cbranch_vccnz .LBB0_304
	global_load_dwordx4 v[78:81], v[88:89], off nt
	global_load_dwordx4 v[234:237], v[88:89], off offset:64 nt
	global_load_dwordx4 v[238:241], v[88:89], off offset:128 nt
	global_load_dwordx4 v[246:249], v[88:89], off offset:192 nt
	s_mov_b64 s[36:37], 0
	s_branch .LBB0_305

; DEVI float lo2f(unsigned u) { return __uint_as_float(u << 16); }
; DEVI float hi2f(unsigned u) { return __uint_as_float(u & 0xffff0000u); }
; DEVI void phase_resid_gemm(const Params& p, const bfu* A, int lda, int nkt, const bfu* wT, int ldb, const float* resid32,
;                            float* ssq_out, float* out32, char* lds) {
;     ...
;         if (resid32) r = *(const float4*)(resid32 + (long)m * 1024 + n);
;         else { const uint2 u = *(const uint2*)(xs + (long)m * LDX + n); r = make_float4(lo2f(u.x), hi2f(u.x), lo2f(u.y), hi2f(u.y)); }
;         float4 o;
;         o.x = r.x + acc[ni][mi][0]; o.y = r.y + acc[ni][mi][1]; o.z = r.z + acc[ni][mi][2]; o.w = r.w + acc[ni][mi][3];
;         if (out32) *(float4*)(out32 + (long)m * 1024 + n) = o;
;         else {
;           uint2 ob; ob.x = pack2(o.x, o.y); ob.y = pack2(o.z, o.w);
;           *(uint2*)(xs + (long)m * LDX + n) = ob;
;           const float q0 = lo2f(ob.x), q1 = hi2f(ob.x), q2 = lo2f(ob.y), q3 = hi2f(ob.y);
.LBB0_307:
	s_waitcnt vmcnt(0)
	v_pk_add_f32 v[78:79], v[82:83], v[78:79]
	v_pk_add_f32 v[80:81], v[84:85], v[80:81]
	v_cvt_pk_bf16_f32 v82, v78, v79
	v_cvt_pk_bf16_f32 v83, v80, v81
	s_and_b64 vcc, exec, s[40:41]
	v_mov_b32_e32 v200, v82
	v_mov_b32_e32 v201, v83
	s_cbranch_vccnz .LBB0_320
	v_mov_b32_e32 v78, v234
	v_mov_b32_e32 v79, v235
	v_mov_b32_e32 v80, v236
	v_mov_b32_e32 v81, v237
	s_cbranch_execnz .LBB0_310

; DEVI float lo2f(unsigned u) { return __uint_as_float(u << 16); }
; DEVI float hi2f(unsigned u) { return __uint_as_float(u & 0xffff0000u); }
; DEVI void phase_resid_gemm(const Params& p, const bfu* A, int lda, int nkt, const bfu* wT, int ldb, const float* resid32,
;                            float* ssq_out, float* out32, char* lds) {
;     ...
;         if (resid32) r = *(const float4*)(resid32 + (long)m * 1024 + n);
;         else { const uint2 u = *(const uint2*)(xs + (long)m * LDX + n); r = make_float4(lo2f(u.x), hi2f(u.x), lo2f(u.y), hi2f(u.y)); }
;         float4 o;
;         o.x = r.x + acc[ni][mi][0]; o.y = r.y + acc[ni][mi][1]; o.z = r.z + acc[ni][mi][2]; o.w = r.w + acc[ni][mi][3];
;         if (out32) *(float4*)(out32 + (long)m * 1024 + n) = o;
;         else {
;           uint2 ob; ob.x = pack2(o.x, o.y); ob.y = pack2(o.z, o.w);
;           *(uint2*)(xs + (long)m * LDX + n) = ob;
;           const float q0 = lo2f(ob.x), q1 = hi2f(ob.x), q2 = lo2f(ob.y), q3 = hi2f(ob.y);
.LBB0_310:
	s_waitcnt vmcnt(0)
	v_pk_add_f32 v[74:75], v[74:75], v[78:79]
	v_pk_add_f32 v[76:77], v[76:77], v[80:81]
	v_cvt_pk_bf16_f32 v78, v74, v75
	v_cvt_pk_bf16_f32 v79, v76, v77
	s_and_b64 vcc, exec, s[40:41]
	v_mov_b32_e32 v206, v78
	v_mov_b32_e32 v207, v79
	v_mov_b32_e32 v204, v200
	v_mov_b32_e32 v205, v201
	v_lshl_add_u64 v[212:213], v[86:87], 0, v[254:255]
	s_nop 0
	v_permlane16_swap_b32_e32 v204, v206
	v_permlane16_swap_b32_e32 v205, v207
	s_nop 1
	global_store_dwordx4 v[212:213], v[204:207], off
	s_cbranch_vccnz .LBB0_321
	v_mov_b32_e32 v74, v238
	v_mov_b32_e32 v75, v239
	v_mov_b32_e32 v76, v240
	v_mov_b32_e32 v77, v241
	s_cbranch_execnz .LBB0_313

; DEVI float lo2f(unsigned u) { return __uint_as_float(u << 16); }
; DEVI float hi2f(unsigned u) { return __uint_as_float(u & 0xffff0000u); }
; DEVI void phase_resid_gemm(const Params& p, const bfu* A, int lda, int nkt, const bfu* wT, int ldb, const float* resid32,
;                            float* ssq_out, float* out32, char* lds) {
;     ...
;         if (resid32) r = *(const float4*)(resid32 + (long)m * 1024 + n);
;         else { const uint2 u = *(const uint2*)(xs + (long)m * LDX + n); r = make_float4(lo2f(u.x), hi2f(u.x), lo2f(u.y), hi2f(u.y)); }
;         float4 o;
;         o.x = r.x + acc[ni][mi][0]; o.y = r.y + acc[ni][mi][1]; o.z = r.z + acc[ni][mi][2]; o.w = r.w + acc[ni][mi][3];
;         if (out32) *(float4*)(out32 + (long)m * 1024 + n) = o;
;         else {
;           uint2 ob; ob.x = pack2(o.x, o.y); ob.y = pack2(o.z, o.w);
;           *(uint2*)(xs + (long)m * LDX + n) = ob;
;           const float q0 = lo2f(ob.x), q1 = hi2f(ob.x), q2 = lo2f(ob.y), q3 = hi2f(ob.y);
.LBB0_313:
	s_waitcnt vmcnt(0)
	v_pk_add_f32 v[70:71], v[70:71], v[74:75]
	v_pk_add_f32 v[72:73], v[72:73], v[76:77]
	v_cvt_pk_bf16_f32 v74, v70, v71
	v_cvt_pk_bf16_f32 v75, v72, v73
	s_and_b64 vcc, exec, s[40:41]
	v_mov_b32_e32 v200, v74
	v_mov_b32_e32 v201, v75
	s_cbranch_vccnz .LBB0_322
	v_mov_b32_e32 v70, v246
	v_mov_b32_e32 v71, v247
	v_mov_b32_e32 v72, v248
	v_mov_b32_e32 v73, v249
	s_cbranch_execnz .LBB0_316

; DEVI void phase_resid_gemm(const Params& p, const bfu* A, int lda, int nkt, const bfu* wT, int ldb, const float* resid32,
;                            float* ssq_out, float* out32, char* lds) {
;     ...
;     for (int mi = 0; mi < 8; ++mi) {
;       const int m = m0 + wm * 128 + mi * 16 + fr;
;       float ss = 0.f;
; #pragma unroll
;       for (int ni = 0; ni < 4; ++ni) {
;         const int n = n0 + wn * 64 + ni * 16 + fq * 4;
;         float4 r;
;         if (resid32) r = *(const float4*)(resid32 + (long)m * 1024 + n);
.LBB0_318:
	s_or_b64 exec, exec, s[36:37]
	v_or_b32_e32 v70, 64, v132
	v_ashrrev_i32_e32 v71, 31, v70
	s_waitcnt lgkmcnt(0)
	v_lshlrev_b64 v[62:63], 12, v[70:71]
	v_lshl_add_u64 v[62:63], s[0:1], 0, v[62:63]
	s_and_b64 vcc, exec, s[40:41]
	v_lshl_add_u64 v[72:73], v[130:131], 2, v[62:63]
	s_cbranch_vccnz .LBB0_323
	global_load_dwordx4 v[62:65], v[72:73], off nt
	global_load_dwordx4 v[234:237], v[72:73], off offset:64 nt
	global_load_dwordx4 v[238:241], v[72:73], off offset:128 nt
	global_load_dwordx4 v[246:249], v[72:73], off offset:192 nt
	s_mov_b64 s[36:37], 0
	s_branch .LBB0_324

; DEVI float lo2f(unsigned u) { return __uint_as_float(u << 16); }
; DEVI float hi2f(unsigned u) { return __uint_as_float(u & 0xffff0000u); }
; DEVI void phase_resid_gemm(const Params& p, const bfu* A, int lda, int nkt, const bfu* wT, int ldb, const float* resid32,
;                            float* ssq_out, float* out32, char* lds) {
;     ...
;         if (resid32) r = *(const float4*)(resid32 + (long)m * 1024 + n);
;         else { const uint2 u = *(const uint2*)(xs + (long)m * LDX + n); r = make_float4(lo2f(u.x), hi2f(u.x), lo2f(u.y), hi2f(u.y)); }
;         float4 o;
;         o.x = r.x + acc[ni][mi][0]; o.y = r.y + acc[ni][mi][1]; o.z = r.z + acc[ni][mi][2]; o.w = r.w + acc[ni][mi][3];
;         if (out32) *(float4*)(out32 + (long)m * 1024 + n) = o;
;         else {
;           uint2 ob; ob.x = pack2(o.x, o.y); ob.y = pack2(o.z, o.w);
;           *(uint2*)(xs + (long)m * LDX + n) = ob;
;           const float q0 = lo2f(ob.x), q1 = hi2f(ob.x), q2 = lo2f(ob.y), q3 = hi2f(ob.y);
.LBB0_326:
	s_waitcnt vmcnt(0)
	v_pk_add_f32 v[62:63], v[66:67], v[62:63]
	v_pk_add_f32 v[64:65], v[68:69], v[64:65]
	v_cvt_pk_bf16_f32 v66, v62, v63
	v_cvt_pk_bf16_f32 v67, v64, v65
	s_and_b64 vcc, exec, s[40:41]
	v_mov_b32_e32 v200, v66
	v_mov_b32_e32 v201, v67
	s_cbranch_vccnz .LBB0_339
	v_mov_b32_e32 v62, v234
	v_mov_b32_e32 v63, v235
	v_mov_b32_e32 v64, v236
	v_mov_b32_e32 v65, v237
	s_cbranch_execnz .LBB0_329

; DEVI float lo2f(unsigned u) { return __uint_as_float(u << 16); }
; DEVI float hi2f(unsigned u) { return __uint_as_float(u & 0xffff0000u); }
; DEVI void phase_resid_gemm(const Params& p, const bfu* A, int lda, int nkt, const bfu* wT, int ldb, const float* resid32,
;                            float* ssq_out, float* out32, char* lds) {
;     ...
;         if (resid32) r = *(const float4*)(resid32 + (long)m * 1024 + n);
;         else { const uint2 u = *(const uint2*)(xs + (long)m * LDX + n); r = make_float4(lo2f(u.x), hi2f(u.x), lo2f(u.y), hi2f(u.y)); }
;         float4 o;
;         o.x = r.x + acc[ni][mi][0]; o.y = r.y + acc[ni][mi][1]; o.z = r.z + acc[ni][mi][2]; o.w = r.w + acc[ni][mi][3];
;         if (out32) *(float4*)(out32 + (long)m * 1024 + n) = o;
;         else {
;           uint2 ob; ob.x = pack2(o.x, o.y); ob.y = pack2(o.z, o.w);
;           *(uint2*)(xs + (long)m * LDX + n) = ob;
;           const float q0 = lo2f(ob.x), q1 = hi2f(ob.x), q2 = lo2f(ob.y), q3 = hi2f(ob.y);
.LBB0_329:
	s_waitcnt vmcnt(0)
	v_pk_add_f32 v[58:59], v[58:59], v[62:63]
	v_pk_add_f32 v[60:61], v[60:61], v[64:65]
	v_cvt_pk_bf16_f32 v62, v58, v59
	v_cvt_pk_bf16_f32 v63, v60, v61
	s_and_b64 vcc, exec, s[40:41]
	v_mov_b32_e32 v206, v62
	v_mov_b32_e32 v207, v63
	v_mov_b32_e32 v204, v200
	v_mov_b32_e32 v205, v201
	v_lshl_add_u64 v[212:213], v[70:71], 0, v[254:255]
	s_nop 0
	v_permlane16_swap_b32_e32 v204, v206
	v_permlane16_swap_b32_e32 v205, v207
	s_nop 1
	global_store_dwordx4 v[212:213], v[204:207], off
	s_cbranch_vccnz .LBB0_340
	v_mov_b32_e32 v58, v238
	v_mov_b32_e32 v59, v239
	v_mov_b32_e32 v60, v240
	v_mov_b32_e32 v61, v241
	s_cbranch_execnz .LBB0_332

; DEVI float lo2f(unsigned u) { return __uint_as_float(u << 16); }
; DEVI float hi2f(unsigned u) { return __uint_as_float(u & 0xffff0000u); }
; DEVI void phase_resid_gemm(const Params& p, const bfu* A, int lda, int nkt, const bfu* wT, int ldb, const float* resid32,
;                            float* ssq_out, float* out32, char* lds) {
;     ...
;         if (resid32) r = *(const float4*)(resid32 + (long)m * 1024 + n);
;         else { const uint2 u = *(const uint2*)(xs + (long)m * LDX + n); r = make_float4(lo2f(u.x), hi2f(u.x), lo2f(u.y), hi2f(u.y)); }
;         float4 o;
;         o.x = r.x + acc[ni][mi][0]; o.y = r.y + acc[ni][mi][1]; o.z = r.z + acc[ni][mi][2]; o.w = r.w + acc[ni][mi][3];
;         if (out32) *(float4*)(out32 + (long)m * 1024 + n) = o;
;         else {
;           uint2 ob; ob.x = pack2(o.x, o.y); ob.y = pack2(o.z, o.w);
;           *(uint2*)(xs + (long)m * LDX + n) = ob;
;           const float q0 = lo2f(ob.x), q1 = hi2f(ob.x), q2 = lo2f(ob.y), q3 = hi2f(ob.y);
.LBB0_332:
	s_waitcnt vmcnt(0)
	v_pk_add_f32 v[54:55], v[54:55], v[58:59]
	v_pk_add_f32 v[56:57], v[56:57], v[60:61]
	v_cvt_pk_bf16_f32 v58, v54, v55
	v_cvt_pk_bf16_f32 v59, v56, v57
	s_and_b64 vcc, exec, s[40:41]
	v_mov_b32_e32 v200, v58
	v_mov_b32_e32 v201, v59
	s_cbranch_vccnz .LBB0_341
	v_mov_b32_e32 v54, v246
	v_mov_b32_e32 v55, v247
	v_mov_b32_e32 v56, v248
	v_mov_b32_e32 v57, v249
	s_cbranch_execnz .LBB0_335

; DEVI void phase_resid_gemm(const Params& p, const bfu* A, int lda, int nkt, const bfu* wT, int ldb, const float* resid32,
;                            float* ssq_out, float* out32, char* lds) {
;     ...
;     for (int mi = 0; mi < 8; ++mi) {
;       const int m = m0 + wm * 128 + mi * 16 + fr;
;       float ss = 0.f;
; #pragma unroll
;       for (int ni = 0; ni < 4; ++ni) {
;         const int n = n0 + wn * 64 + ni * 16 + fq * 4;
;         float4 r;
;         if (resid32) r = *(const float4*)(resid32 + (long)m * 1024 + n);
.LBB0_337:
	s_or_b64 exec, exec, s[36:37]
	v_or_b32_e32 v54, 0x50, v132
	v_ashrrev_i32_e32 v55, 31, v54
	s_waitcnt lgkmcnt(0)
	v_lshlrev_b64 v[46:47], 12, v[54:55]
	v_lshl_add_u64 v[46:47], s[0:1], 0, v[46:47]
	s_and_b64 vcc, exec, s[40:41]
	v_lshl_add_u64 v[56:57], v[130:131], 2, v[46:47]
	s_cbranch_vccnz .LBB0_342
	global_load_dwordx4 v[46:49], v[56:57], off nt
	global_load_dwordx4 v[234:237], v[56:57], off offset:64 nt
	global_load_dwordx4 v[238:241], v[56:57], off offset:128 nt
	global_load_dwordx4 v[246:249], v[56:57], off offset:192 nt
	s_mov_b64 s[36:37], 0
	s_branch .LBB0_343

; DEVI float lo2f(unsigned u) { return __uint_as_float(u << 16); }
; DEVI float hi2f(unsigned u) { return __uint_as_float(u & 0xffff0000u); }
; DEVI void phase_resid_gemm(const Params& p, const bfu* A, int lda, int nkt, const bfu* wT, int ldb, const float* resid32,
;                            float* ssq_out, float* out32, char* lds) {
;     ...
;         if (resid32) r = *(const float4*)(resid32 + (long)m * 1024 + n);
;         else { const uint2 u = *(const uint2*)(xs + (long)m * LDX + n); r = make_float4(lo2f(u.x), hi2f(u.x), lo2f(u.y), hi2f(u.y)); }
;         float4 o;
;         o.x = r.x + acc[ni][mi][0]; o.y = r.y + acc[ni][mi][1]; o.z = r.z + acc[ni][mi][2]; o.w = r.w + acc[ni][mi][3];
;         if (out32) *(float4*)(out32 + (long)m * 1024 + n) = o;
;         else {
;           uint2 ob; ob.x = pack2(o.x, o.y); ob.y = pack2(o.z, o.w);
;           *(uint2*)(xs + (long)m * LDX + n) = ob;
;           const float q0 = lo2f(ob.x), q1 = hi2f(ob.x), q2 = lo2f(ob.y), q3 = hi2f(ob.y);
.LBB0_345:
	s_waitcnt vmcnt(0)
	v_pk_add_f32 v[46:47], v[50:51], v[46:47]
	v_pk_add_f32 v[48:49], v[52:53], v[48:49]
	v_cvt_pk_bf16_f32 v50, v46, v47
	v_cvt_pk_bf16_f32 v51, v48, v49
	s_and_b64 vcc, exec, s[40:41]
	v_mov_b32_e32 v200, v50
	v_mov_b32_e32 v201, v51
	s_cbranch_vccnz .LBB0_358
	v_mov_b32_e32 v46, v234
	v_mov_b32_e32 v47, v235
	v_mov_b32_e32 v48, v236
	v_mov_b32_e32 v49, v237
	s_cbranch_execnz .LBB0_348

; DEVI float lo2f(unsigned u) { return __uint_as_float(u << 16); }
; DEVI float hi2f(unsigned u) { return __uint_as_float(u & 0xffff0000u); }
; DEVI void phase_resid_gemm(const Params& p, const bfu* A, int lda, int nkt, const bfu* wT, int ldb, const float* resid32,
;                            float* ssq_out, float* out32, char* lds) {
;     ...
;         if (resid32) r = *(const float4*)(resid32 + (long)m * 1024 + n);
;         else { const uint2 u = *(const uint2*)(xs + (long)m * LDX + n); r = make_float4(lo2f(u.x), hi2f(u.x), lo2f(u.y), hi2f(u.y)); }
;         float4 o;
;         o.x = r.x + acc[ni][mi][0]; o.y = r.y + acc[ni][mi][1]; o.z = r.z + acc[ni][mi][2]; o.w = r.w + acc[ni][mi][3];
;         if (out32) *(float4*)(out32 + (long)m * 1024 + n) = o;
;         else {
;           uint2 ob; ob.x = pack2(o.x, o.y); ob.y = pack2(o.z, o.w);
;           *(uint2*)(xs + (long)m * LDX + n) = ob;
;           const float q0 = lo2f(ob.x), q1 = hi2f(ob.x), q2 = lo2f(ob.y), q3 = hi2f(ob.y);
.LBB0_348:
	s_waitcnt vmcnt(0)
	v_pk_add_f32 v[42:43], v[42:43], v[46:47]
	v_pk_add_f32 v[44:45], v[44:45], v[48:49]
	v_cvt_pk_bf16_f32 v46, v42, v43
	v_cvt_pk_bf16_f32 v47, v44, v45
	s_and_b64 vcc, exec, s[40:41]
	v_mov_b32_e32 v206, v46
	v_mov_b32_e32 v207, v47
	v_mov_b32_e32 v204, v200
	v_mov_b32_e32 v205, v201
	v_lshl_add_u64 v[212:213], v[54:55], 0, v[254:255]
	s_nop 0
	v_permlane16_swap_b32_e32 v204, v206
	v_permlane16_swap_b32_e32 v205, v207
	s_nop 1
	global_store_dwordx4 v[212:213], v[204:207], off
	s_cbranch_vccnz .LBB0_359
	v_mov_b32_e32 v42, v238
	v_mov_b32_e32 v43, v239
	v_mov_b32_e32 v44, v240
	v_mov_b32_e32 v45, v241
	s_cbranch_execnz .LBB0_351

; DEVI float lo2f(unsigned u) { return __uint_as_float(u << 16); }
; DEVI float hi2f(unsigned u) { return __uint_as_float(u & 0xffff0000u); }
; DEVI void phase_resid_gemm(const Params& p, const bfu* A, int lda, int nkt, const bfu* wT, int ldb, const float* resid32,
;                            float* ssq_out, float* out32, char* lds) {
;     ...
;         if (resid32) r = *(const float4*)(resid32 + (long)m * 1024 + n);
;         else { const uint2 u = *(const uint2*)(xs + (long)m * LDX + n); r = make_float4(lo2f(u.x), hi2f(u.x), lo2f(u.y), hi2f(u.y)); }
;         float4 o;
;         o.x = r.x + acc[ni][mi][0]; o.y = r.y + acc[ni][mi][1]; o.z = r.z + acc[ni][mi][2]; o.w = r.w + acc[ni][mi][3];
;         if (out32) *(float4*)(out32 + (long)m * 1024 + n) = o;
;         else {
;           uint2 ob; ob.x = pack2(o.x, o.y); ob.y = pack2(o.z, o.w);
;           *(uint2*)(xs + (long)m * LDX + n) = ob;
;           const float q0 = lo2f(ob.x), q1 = hi2f(ob.x), q2 = lo2f(ob.y), q3 = hi2f(ob.y);
.LBB0_351:
	s_waitcnt vmcnt(0)
	v_pk_add_f32 v[38:39], v[38:39], v[42:43]
	v_pk_add_f32 v[40:41], v[40:41], v[44:45]
	v_cvt_pk_bf16_f32 v42, v38, v39
	v_cvt_pk_bf16_f32 v43, v40, v41
	s_and_b64 vcc, exec, s[40:41]
	v_mov_b32_e32 v200, v42
	v_mov_b32_e32 v201, v43
	s_cbranch_vccnz .LBB0_360
	v_mov_b32_e32 v38, v246
	v_mov_b32_e32 v39, v247
	v_mov_b32_e32 v40, v248
	v_mov_b32_e32 v41, v249
	s_cbranch_execnz .LBB0_354

; DEVI void phase_resid_gemm(const Params& p, const bfu* A, int lda, int nkt, const bfu* wT, int ldb, const float* resid32,
;                            float* ssq_out, float* out32, char* lds) {
;     ...
;     for (int mi = 0; mi < 8; ++mi) {
;       const int m = m0 + wm * 128 + mi * 16 + fr;
;       float ss = 0.f;
; #pragma unroll
;       for (int ni = 0; ni < 4; ++ni) {
;         const int n = n0 + wn * 64 + ni * 16 + fq * 4;
;         float4 r;
;         if (resid32) r = *(const float4*)(resid32 + (long)m * 1024 + n);
.LBB0_356:
	s_or_b64 exec, exec, s[36:37]
	v_or_b32_e32 v38, 0x60, v132
	v_ashrrev_i32_e32 v39, 31, v38
	s_waitcnt lgkmcnt(0)
	v_lshlrev_b64 v[30:31], 12, v[38:39]
	v_lshl_add_u64 v[30:31], s[0:1], 0, v[30:31]
	s_and_b64 vcc, exec, s[40:41]
	v_lshl_add_u64 v[40:41], v[130:131], 2, v[30:31]
	s_cbranch_vccnz .LBB0_361
	global_load_dwordx4 v[30:33], v[40:41], off nt
	global_load_dwordx4 v[234:237], v[40:41], off offset:64 nt
	global_load_dwordx4 v[238:241], v[40:41], off offset:128 nt
	global_load_dwordx4 v[246:249], v[40:41], off offset:192 nt
	s_mov_b64 s[36:37], 0
	s_branch .LBB0_362

; DEVI float lo2f(unsigned u) { return __uint_as_float(u << 16); }
; DEVI float hi2f(unsigned u) { return __uint_as_float(u & 0xffff0000u); }
; DEVI void phase_resid_gemm(const Params& p, const bfu* A, int lda, int nkt, const bfu* wT, int ldb, const float* resid32,
;                            float* ssq_out, float* out32, char* lds) {
;     ...
;         if (resid32) r = *(const float4*)(resid32 + (long)m * 1024 + n);
;         else { const uint2 u = *(const uint2*)(xs + (long)m * LDX + n); r = make_float4(lo2f(u.x), hi2f(u.x), lo2f(u.y), hi2f(u.y)); }
;         float4 o;
;         o.x = r.x + acc[ni][mi][0]; o.y = r.y + acc[ni][mi][1]; o.z = r.z + acc[ni][mi][2]; o.w = r.w + acc[ni][mi][3];
;         if (out32) *(float4*)(out32 + (long)m * 1024 + n) = o;
;         else {
;           uint2 ob; ob.x = pack2(o.x, o.y); ob.y = pack2(o.z, o.w);
;           *(uint2*)(xs + (long)m * LDX + n) = ob;
;           const float q0 = lo2f(ob.x), q1 = hi2f(ob.x), q2 = lo2f(ob.y), q3 = hi2f(ob.y);
.LBB0_364:
	s_waitcnt vmcnt(0)
	v_pk_add_f32 v[30:31], v[34:35], v[30:31]
	v_pk_add_f32 v[32:33], v[36:37], v[32:33]
	v_cvt_pk_bf16_f32 v34, v30, v31
	v_cvt_pk_bf16_f32 v35, v32, v33
	s_and_b64 vcc, exec, s[40:41]
	v_mov_b32_e32 v200, v34
	v_mov_b32_e32 v201, v35
	s_cbranch_vccnz .LBB0_377
	v_mov_b32_e32 v30, v234
	v_mov_b32_e32 v31, v235
	v_mov_b32_e32 v32, v236
	v_mov_b32_e32 v33, v237
	s_cbranch_execnz .LBB0_367

; DEVI float lo2f(unsigned u) { return __uint_as_float(u << 16); }
; DEVI float hi2f(unsigned u) { return __uint_as_float(u & 0xffff0000u); }
; DEVI void phase_resid_gemm(const Params& p, const bfu* A, int lda, int nkt, const bfu* wT, int ldb, const float* resid32,
;                            float* ssq_out, float* out32, char* lds) {
;     ...
;         if (resid32) r = *(const float4*)(resid32 + (long)m * 1024 + n);
;         else { const uint2 u = *(const uint2*)(xs + (long)m * LDX + n); r = make_float4(lo2f(u.x), hi2f(u.x), lo2f(u.y), hi2f(u.y)); }
;         float4 o;
;         o.x = r.x + acc[ni][mi][0]; o.y = r.y + acc[ni][mi][1]; o.z = r.z + acc[ni][mi][2]; o.w = r.w + acc[ni][mi][3];
;         if (out32) *(float4*)(out32 + (long)m * 1024 + n) = o;
;         else {
;           uint2 ob; ob.x = pack2(o.x, o.y); ob.y = pack2(o.z, o.w);
;           *(uint2*)(xs + (long)m * LDX + n) = ob;
;           const float q0 = lo2f(ob.x), q1 = hi2f(ob.x), q2 = lo2f(ob.y), q3 = hi2f(ob.y);
.LBB0_367:
	s_waitcnt vmcnt(0)
	v_pk_add_f32 v[26:27], v[26:27], v[30:31]
	v_pk_add_f32 v[28:29], v[28:29], v[32:33]
	v_cvt_pk_bf16_f32 v30, v26, v27
	v_cvt_pk_bf16_f32 v31, v28, v29
	s_and_b64 vcc, exec, s[40:41]
	v_mov_b32_e32 v206, v30
	v_mov_b32_e32 v207, v31
	v_mov_b32_e32 v204, v200
	v_mov_b32_e32 v205, v201
	v_lshl_add_u64 v[212:213], v[38:39], 0, v[254:255]
	s_nop 0
	v_permlane16_swap_b32_e32 v204, v206
	v_permlane16_swap_b32_e32 v205, v207
	s_nop 1
	global_store_dwordx4 v[212:213], v[204:207], off
	s_cbranch_vccnz .LBB0_378
	v_mov_b32_e32 v26, v238
	v_mov_b32_e32 v27, v239
	v_mov_b32_e32 v28, v240
	v_mov_b32_e32 v29, v241
	s_cbranch_execnz .LBB0_370

; DEVI float lo2f(unsigned u) { return __uint_as_float(u << 16); }
; DEVI float hi2f(unsigned u) { return __uint_as_float(u & 0xffff0000u); }
; DEVI void phase_resid_gemm(const Params& p, const bfu* A, int lda, int nkt, const bfu* wT, int ldb, const float* resid32,
;                            float* ssq_out, float* out32, char* lds) {
;     ...
;         if (resid32) r = *(const float4*)(resid32 + (long)m * 1024 + n);
;         else { const uint2 u = *(const uint2*)(xs + (long)m * LDX + n); r = make_float4(lo2f(u.x), hi2f(u.x), lo2f(u.y), hi2f(u.y)); }
;         float4 o;
;         o.x = r.x + acc[ni][mi][0]; o.y = r.y + acc[ni][mi][1]; o.z = r.z + acc[ni][mi][2]; o.w = r.w + acc[ni][mi][3];
;         if (out32) *(float4*)(out32 + (long)m * 1024 + n) = o;
;         else {
;           uint2 ob; ob.x = pack2(o.x, o.y); ob.y = pack2(o.z, o.w);
;           *(uint2*)(xs + (long)m * LDX + n) = ob;
;           const float q0 = lo2f(ob.x), q1 = hi2f(ob.x), q2 = lo2f(ob.y), q3 = hi2f(ob.y);
.LBB0_370:
	s_waitcnt vmcnt(0)
	v_pk_add_f32 v[22:23], v[22:23], v[26:27]
	v_pk_add_f32 v[24:25], v[24:25], v[28:29]
	v_cvt_pk_bf16_f32 v26, v22, v23
	v_cvt_pk_bf16_f32 v27, v24, v25
	s_and_b64 vcc, exec, s[40:41]
	v_mov_b32_e32 v200, v26
	v_mov_b32_e32 v201, v27
	s_cbranch_vccnz .LBB0_379
	v_mov_b32_e32 v22, v246
	v_mov_b32_e32 v23, v247
	v_mov_b32_e32 v24, v248
	v_mov_b32_e32 v25, v249
	s_cbranch_execnz .LBB0_373

; DEVI void phase_resid_gemm(const Params& p, const bfu* A, int lda, int nkt, const bfu* wT, int ldb, const float* resid32,
;                            float* ssq_out, float* out32, char* lds) {
;     ...
;     for (int mi = 0; mi < 8; ++mi) {
;       const int m = m0 + wm * 128 + mi * 16 + fr;
;       float ss = 0.f;
; #pragma unroll
;       for (int ni = 0; ni < 4; ++ni) {
;         const int n = n0 + wn * 64 + ni * 16 + fq * 4;
;         float4 r;
;         if (resid32) r = *(const float4*)(resid32 + (long)m * 1024 + n);
.LBB0_375:
	s_or_b64 exec, exec, s[36:37]
	v_or_b32_e32 v22, 0x70, v132
	v_ashrrev_i32_e32 v23, 31, v22
	s_waitcnt lgkmcnt(0)
	v_lshlrev_b64 v[14:15], 12, v[22:23]
	v_lshl_add_u64 v[14:15], s[0:1], 0, v[14:15]
	s_and_b64 vcc, exec, s[40:41]
	v_lshl_add_u64 v[24:25], v[130:131], 2, v[14:15]
	s_cbranch_vccnz .LBB0_380
	global_load_dwordx4 v[14:17], v[24:25], off nt
	global_load_dwordx4 v[234:237], v[24:25], off offset:64 nt
	global_load_dwordx4 v[238:241], v[24:25], off offset:128 nt
	global_load_dwordx4 v[246:249], v[24:25], off offset:192 nt
	s_mov_b64 s[36:37], 0
	s_branch .LBB0_381

; DEVI float lo2f(unsigned u) { return __uint_as_float(u << 16); }
; DEVI float hi2f(unsigned u) { return __uint_as_float(u & 0xffff0000u); }
; DEVI void phase_resid_gemm(const Params& p, const bfu* A, int lda, int nkt, const bfu* wT, int ldb, const float* resid32,
;                            float* ssq_out, float* out32, char* lds) {
;     ...
;         if (resid32) r = *(const float4*)(resid32 + (long)m * 1024 + n);
;         else { const uint2 u = *(const uint2*)(xs + (long)m * LDX + n); r = make_float4(lo2f(u.x), hi2f(u.x), lo2f(u.y), hi2f(u.y)); }
;         float4 o;
;         o.x = r.x + acc[ni][mi][0]; o.y = r.y + acc[ni][mi][1]; o.z = r.z + acc[ni][mi][2]; o.w = r.w + acc[ni][mi][3];
;         if (out32) *(float4*)(out32 + (long)m * 1024 + n) = o;
;         else {
;           uint2 ob; ob.x = pack2(o.x, o.y); ob.y = pack2(o.z, o.w);
;           *(uint2*)(xs + (long)m * LDX + n) = ob;
;           const float q0 = lo2f(ob.x), q1 = hi2f(ob.x), q2 = lo2f(ob.y), q3 = hi2f(ob.y);
.LBB0_383:
	s_waitcnt vmcnt(0)
	v_pk_add_f32 v[14:15], v[18:19], v[14:15]
	v_pk_add_f32 v[16:17], v[20:21], v[16:17]
	v_cvt_pk_bf16_f32 v18, v14, v15
	v_cvt_pk_bf16_f32 v19, v16, v17
	s_and_b64 vcc, exec, s[40:41]
	v_mov_b32_e32 v200, v18
	v_mov_b32_e32 v201, v19
	s_cbranch_vccnz .LBB0_396
	v_mov_b32_e32 v14, v234
	v_mov_b32_e32 v15, v235
	v_mov_b32_e32 v16, v236
	v_mov_b32_e32 v17, v237
	s_cbranch_execnz .LBB0_386

; DEVI float lo2f(unsigned u) { return __uint_as_float(u << 16); }
; DEVI float hi2f(unsigned u) { return __uint_as_float(u & 0xffff0000u); }
; DEVI void phase_resid_gemm(const Params& p, const bfu* A, int lda, int nkt, const bfu* wT, int ldb, const float* resid32,
;                            float* ssq_out, float* out32, char* lds) {
;     ...
;         if (resid32) r = *(const float4*)(resid32 + (long)m * 1024 + n);
;         else { const uint2 u = *(const uint2*)(xs + (long)m * LDX + n); r = make_float4(lo2f(u.x), hi2f(u.x), lo2f(u.y), hi2f(u.y)); }
;         float4 o;
;         o.x = r.x + acc[ni][mi][0]; o.y = r.y + acc[ni][mi][1]; o.z = r.z + acc[ni][mi][2]; o.w = r.w + acc[ni][mi][3];
;         if (out32) *(float4*)(out32 + (long)m * 1024 + n) = o;
;         else {
;           uint2 ob; ob.x = pack2(o.x, o.y); ob.y = pack2(o.z, o.w);
;           *(uint2*)(xs + (long)m * LDX + n) = ob;
;           const float q0 = lo2f(ob.x), q1 = hi2f(ob.x), q2 = lo2f(ob.y), q3 = hi2f(ob.y);
.LBB0_386:
	s_waitcnt vmcnt(0)
	v_pk_add_f32 v[10:11], v[10:11], v[14:15]
	v_pk_add_f32 v[12:13], v[12:13], v[16:17]
	v_cvt_pk_bf16_f32 v14, v10, v11
	v_cvt_pk_bf16_f32 v15, v12, v13
	s_and_b64 vcc, exec, s[40:41]
	v_mov_b32_e32 v206, v14
	v_mov_b32_e32 v207, v15
	v_mov_b32_e32 v204, v200
	v_mov_b32_e32 v205, v201
	v_lshl_add_u64 v[212:213], v[22:23], 0, v[254:255]
	s_nop 0
	v_permlane16_swap_b32_e32 v204, v206
	v_permlane16_swap_b32_e32 v205, v207
	s_nop 1
	global_store_dwordx4 v[212:213], v[204:207], off
	s_cbranch_vccnz .LBB0_397
	v_mov_b32_e32 v10, v238
	v_mov_b32_e32 v11, v239
	v_mov_b32_e32 v12, v240
	v_mov_b32_e32 v13, v241
	s_cbranch_execnz .LBB0_389

; DEVI float lo2f(unsigned u) { return __uint_as_float(u << 16); }
; DEVI float hi2f(unsigned u) { return __uint_as_float(u & 0xffff0000u); }
; DEVI void phase_resid_gemm(const Params& p, const bfu* A, int lda, int nkt, const bfu* wT, int ldb, const float* resid32,
;                            float* ssq_out, float* out32, char* lds) {
;     ...
;         if (resid32) r = *(const float4*)(resid32 + (long)m * 1024 + n);
;         else { const uint2 u = *(const uint2*)(xs + (long)m * LDX + n); r = make_float4(lo2f(u.x), hi2f(u.x), lo2f(u.y), hi2f(u.y)); }
;         float4 o;
;         o.x = r.x + acc[ni][mi][0]; o.y = r.y + acc[ni][mi][1]; o.z = r.z + acc[ni][mi][2]; o.w = r.w + acc[ni][mi][3];
;         if (out32) *(float4*)(out32 + (long)m * 1024 + n) = o;
;         else {
;           uint2 ob; ob.x = pack2(o.x, o.y); ob.y = pack2(o.z, o.w);
;           *(uint2*)(xs + (long)m * LDX + n) = ob;
;           const float q0 = lo2f(ob.x), q1 = hi2f(ob.x), q2 = lo2f(ob.y), q3 = hi2f(ob.y);
.LBB0_389:
	s_waitcnt vmcnt(0)
	v_pk_add_f32 v[6:7], v[6:7], v[10:11]
	v_pk_add_f32 v[8:9], v[8:9], v[12:13]
	v_cvt_pk_bf16_f32 v10, v6, v7
	v_cvt_pk_bf16_f32 v11, v8, v9
	s_and_b64 vcc, exec, s[40:41]
	v_mov_b32_e32 v200, v10
	v_mov_b32_e32 v201, v11
	s_cbranch_vccnz .LBB0_398
	v_mov_b32_e32 v6, v246
	v_mov_b32_e32 v7, v247
	v_mov_b32_e32 v8, v248
	v_mov_b32_e32 v9, v249
	s_cbranch_execnz .LBB0_392
